# k9 plus EpiRes epilogues (P7/P10): all later residual batches touched by prefetch loads at epilogue start so the 3 later load batches hit cache instead of exposing a cold round trip each
# baseline (speedup 1.0000x reference)
; __device__ __forceinline__ unsigned cvtpk(float lo, float hi) { unsigned r; asm volatile("v_cvt_pk_bf16_f32 %0, %1, %2" : "=v"(r) : "v"(lo), "v"(hi)); return r; }
;     __device__ __forceinline__ float* out() const { return (float*)(__attribute__((address_space(1))) float*)get(20); }
;     __device__ __forceinline__ void operator()(const f32x4 (&acc)[2][2][4][2], const Unit& u, int wr, int wc, int fr, int fq) const {
;         const int row0 = u.pm * BM + wr * 64 + fr, col0 = u.pn * BM + wc * 32 + 8 * fq;
; #pragma unroll
;         for (int ai = 0; ai < 2; ++ai)
; #pragma unroll
;             for (int mp = 0; mp < 2; ++mp) {
;                 f32x4 b0[2][2], b1[2][2];
; #pragma unroll
;                 for (int mm = 0; mm < 2; ++mm)
; #pragma unroll
;                     for (int bj = 0; bj < 2; ++bj) { const size_t off = (size_t)(row0 + ai * HALF + (2 * mp + mm) * 16) * 2048 + col0 + bj * HALF;
;                         if (BASE_BF) { const u32x4 w = *(const u32x4*)((const bf16*)base + off);
;                             b0[mm][bj] = (f32x4){bflo(w.x), bfhi(w.x), bflo(w.y), bfhi(w.y)}; b1[mm][bj] = (f32x4){bflo(w.z), bfhi(w.z), bflo(w.w), bfhi(w.w)}; }
;                         else { b0[mm][bj] = __builtin_nontemporal_load((const f32x4*)((const float*)base + off)); b1[mm][bj] = __builtin_nontemporal_load((const f32x4*)((const float*)base + off + 4)); } }
; #pragma unroll
;                 for (int mm = 0; mm < 2; ++mm)
; #pragma unroll
;                     for (int bj = 0; bj < 2; ++bj) { const int m = 2 * mp + mm; const size_t off = (size_t)(row0 + ai * HALF + m * 16) * 2048 + col0 + bj * HALF;
;                         const f32x4 v0 = b0[mm][bj] + acc[ai][bj][m][0], v1 = b1[mm][bj] + acc[ai][bj][m][1];
;                         if (OUT_BF) { u32x4 w; w.x = cvtpk(v0[0], v0[1]); w.y = cvtpk(v0[2], v0[3]); w.z = cvtpk(v1[0], v1[1]); w.w = cvtpk(v1[2], v1[3]); *(u32x4*)((bf16*)out + off) = w; }
;                         else { *(f32x4*)((float*)out + off) = v0; *(f32x4*)((float*)out + off + 4) = v1; } }
;             }
;     }
.LBB0_870:
	v_lshl_add_u32 v150, s54, 8, v152
	v_lshl_or_b32 v144, s55, 8, v154
	v_ashrrev_i32_e32 v145, 31, v144
	v_or_b32_e32 v166, 16, v150
	v_lshlrev_b64 v[144:145], 1, v[144:145]
	v_ashrrev_i32_e32 v151, 31, v150
	v_ashrrev_i32_e32 v167, 31, v166
	v_lshl_add_u64 v[146:147], s[4:5], 0, v[144:145]
	v_lshlrev_b64 v[148:149], 12, v[150:151]
	v_lshlrev_b64 v[174:175], 12, v[166:167]
	v_lshl_add_u64 v[162:163], v[146:147], 0, v[148:149]
	v_lshl_add_u64 v[170:171], v[146:147], 0, v[174:175]
	s_mov_b32 s81, 0
	s_mov_b32 s80, 0x20000
	v_lshl_add_u64 v[248:249], v[162:163], 0, s[80:81]
	global_load_dwordx4 v[198:201], v[248:249], off
	global_load_dwordx4 v[206:209], v[248:249], off offset:256
	s_mov_b32 s80, 0x30000
	v_lshl_add_u64 v[248:249], v[162:163], 0, s[80:81]
	global_load_dwordx4 v[210:213], v[248:249], off
	global_load_dwordx4 v[214:217], v[248:249], off offset:256
	s_mov_b32 s80, 0x80000
	v_lshl_add_u64 v[248:249], v[162:163], 0, s[80:81]
	global_load_dwordx4 v[218:221], v[248:249], off
	global_load_dwordx4 v[222:225], v[248:249], off offset:256
	s_mov_b32 s80, 0x90000
	v_lshl_add_u64 v[248:249], v[162:163], 0, s[80:81]
	global_load_dwordx4 v[226:229], v[248:249], off
	global_load_dwordx4 v[232:235], v[248:249], off offset:256
	s_mov_b32 s80, 0xa0000
	v_lshl_add_u64 v[248:249], v[162:163], 0, s[80:81]
	global_load_dwordx4 v[236:239], v[248:249], off
	global_load_dwordx4 v[240:243], v[248:249], off offset:256
	s_mov_b32 s80, 0xb0000
	v_lshl_add_u64 v[248:249], v[162:163], 0, s[80:81]
	global_load_dwordx4 v[244:247], v[248:249], off
	global_load_dwordx4 v[250:253], v[248:249], off offset:256
	global_load_dwordx4 v[158:161], v[162:163], off
	s_nop 0
	global_load_dwordx4 v[162:165], v[162:163], off offset:256
	s_nop 0
	global_load_dwordx4 v[166:169], v[170:171], off
	s_nop 0
	global_load_dwordx4 v[170:173], v[170:171], off offset:256
	v_lshl_add_u64 v[178:179], s[4:5], 0, v[148:149]
	v_lshl_add_u64 v[178:179], v[178:179], 0, v[144:145]
	v_or_b32_e32 v176, 32, v150
	v_ashrrev_i32_e32 v177, 31, v176
	v_lshlrev_b64 v[176:177], 12, v[176:177]
	v_lshl_add_u64 v[174:175], s[4:5], 0, v[174:175]
	v_lshl_add_u64 v[180:181], v[146:147], 0, v[176:177]
	v_lshl_add_u64 v[174:175], v[174:175], 0, v[144:145]
	s_andn2_b64 vcc, exec, s[0:1]
	s_mov_b64 s[0:1], -1
	s_waitcnt vmcnt(0)
	v_lshlrev_b32_e32 v182, 16, v158
	v_and_b32_e32 v183, 0xffff0000, v158
	v_lshlrev_b32_e32 v184, 16, v160
	v_and_b32_e32 v185, 0xffff0000, v160
	v_lshlrev_b32_e32 v160, 16, v161
	v_and_b32_e32 v161, 0xffff0000, v161
	v_lshlrev_b32_e32 v186, 16, v162
	v_and_b32_e32 v187, 0xffff0000, v162
	v_lshlrev_b32_e32 v196, 16, v172
	v_and_b32_e32 v197, 0xffff0000, v172
	v_lshlrev_b32_e32 v158, 16, v159
	v_and_b32_e32 v159, 0xffff0000, v159
	v_lshlrev_b32_e32 v172, 16, v173
	v_and_b32_e32 v173, 0xffff0000, v173
	v_pk_add_f32 v[124:125], v[124:125], v[182:183]
	v_pk_add_f32 v[122:123], v[122:123], v[160:161]
	v_pk_add_f32 v[108:109], v[108:109], v[186:187]
	v_pk_add_f32 v[160:161], v[96:97], v[196:197]
	v_cvt_pk_bf16_f32 v96, v124, v125
	v_lshlrev_b32_e32 v190, 16, v166
	v_and_b32_e32 v191, 0xffff0000, v166
	v_pk_add_f32 v[126:127], v[126:127], v[158:159]
	v_pk_add_f32 v[120:121], v[120:121], v[184:185]
	v_pk_add_f32 v[158:159], v[98:99], v[172:173]
	v_cvt_pk_bf16_f32 v97, v126, v127
	v_cvt_pk_bf16_f32 v98, v120, v121
	v_cvt_pk_bf16_f32 v99, v122, v123
	global_store_dwordx4 v[178:179], v[96:99], off
	v_lshlrev_b32_e32 v162, 16, v163
	v_and_b32_e32 v163, 0xffff0000, v163
	v_cvt_pk_bf16_f32 v96, v108, v109
	v_or_b32_e32 v108, 48, v150
	v_lshlrev_b32_e32 v188, 16, v164
	v_and_b32_e32 v189, 0xffff0000, v164
	v_lshlrev_b32_e32 v164, 16, v165
	v_and_b32_e32 v165, 0xffff0000, v165
	v_lshlrev_b32_e32 v192, 16, v168
	v_and_b32_e32 v193, 0xffff0000, v168
	v_pk_add_f32 v[116:117], v[116:117], v[190:191]
	v_ashrrev_i32_e32 v109, 31, v108
	v_lshlrev_b32_e32 v166, 16, v167
	v_and_b32_e32 v167, 0xffff0000, v167
	v_lshlrev_b32_e32 v168, 16, v169
	v_and_b32_e32 v169, 0xffff0000, v169
	v_lshlrev_b32_e32 v194, 16, v170
	v_and_b32_e32 v195, 0xffff0000, v170
	v_lshlrev_b32_e32 v170, 16, v171
	v_and_b32_e32 v171, 0xffff0000, v171
	v_pk_add_f32 v[110:111], v[110:111], v[162:163]
	v_pk_add_f32 v[106:107], v[106:107], v[164:165]
	v_pk_add_f32 v[104:105], v[104:105], v[188:189]
	v_pk_add_f32 v[112:113], v[112:113], v[192:193]
	v_cvt_pk_bf16_f32 v97, v110, v111
	v_cvt_pk_bf16_f32 v98, v104, v105
	v_cvt_pk_bf16_f32 v99, v106, v107
	global_store_dwordx4 v[178:179], v[96:99], off offset:256
	v_pk_add_f32 v[118:119], v[118:119], v[166:167]
	v_pk_add_f32 v[114:115], v[114:115], v[168:169]
	v_cvt_pk_bf16_f32 v96, v116, v117
	v_lshlrev_b64 v[116:117], 12, v[108:109]
	v_pk_add_f32 v[102:103], v[102:103], v[170:171]
	v_pk_add_f32 v[100:101], v[100:101], v[194:195]
	v_cvt_pk_bf16_f32 v97, v118, v119
	v_cvt_pk_bf16_f32 v98, v112, v113
	v_cvt_pk_bf16_f32 v99, v114, v115
	v_lshl_add_u64 v[112:113], v[146:147], 0, v[116:117]
	global_store_dwordx4 v[174:175], v[96:99], off
	v_lshl_add_u64 v[120:121], s[4:5], 0, v[176:177]
	v_lshl_add_u64 v[120:121], v[120:121], 0, v[144:145]
	v_cvt_pk_bf16_f32 v96, v100, v101
	v_cvt_pk_bf16_f32 v97, v102, v103
	v_cvt_pk_bf16_f32 v98, v160, v161
	v_cvt_pk_bf16_f32 v99, v158, v159
	global_load_dwordx4 v[100:103], v[180:181], off
	global_load_dwordx4 v[104:107], v[180:181], off offset:256
	global_load_dwordx4 v[108:111], v[112:113], off
	s_nop 0
	global_load_dwordx4 v[112:115], v[112:113], off offset:256
	v_lshl_add_u64 v[118:119], v[148:149], 0, s[10:11]
	global_store_dwordx4 v[174:175], v[96:99], off offset:256
	v_lshl_add_u64 v[116:117], s[4:5], 0, v[116:117]
	v_lshl_add_u64 v[122:123], v[146:147], 0, v[118:119]
	v_lshl_add_u64 v[116:117], v[116:117], 0, v[144:145]
	s_waitcnt vmcnt(4)
; __device__ __forceinline__ unsigned cvtpk(float lo, float hi) { unsigned r; asm volatile("v_cvt_pk_bf16_f32 %0, %1, %2" : "=v"(r) : "v"(lo), "v"(hi)); return r; }
;     __device__ __forceinline__ float* out() const { return (float*)(__attribute__((address_space(1))) float*)get(20); }
;     __device__ __forceinline__ void operator()(const f32x4 (&acc)[2][2][4][2], const Unit& u, int wr, int wc, int fr, int fq) const {
;     ...
;             for (int mp = 0; mp < 2; ++mp) {
;                 f32x4 b0[2][2], b1[2][2];
; #pragma unroll
;                 for (int mm = 0; mm < 2; ++mm)
; #pragma unroll
;                     for (int bj = 0; bj < 2; ++bj) { const size_t off = (size_t)(row0 + ai * HALF + (2 * mp + mm) * 16) * 2048 + col0 + bj * HALF;
;                         if (BASE_BF) { const u32x4 w = *(const u32x4*)((const bf16*)base + off);
;                             b0[mm][bj] = (f32x4){bflo(w.x), bfhi(w.x), bflo(w.y), bfhi(w.y)}; b1[mm][bj] = (f32x4){bflo(w.z), bfhi(w.z), bflo(w.w), bfhi(w.w)}; }
;                         else { b0[mm][bj] = __builtin_nontemporal_load((const f32x4*)((const float*)base + off)); b1[mm][bj] = __builtin_nontemporal_load((const f32x4*)((const float*)base + off + 4)); } }
; #pragma unroll
;                 for (int mm = 0; mm < 2; ++mm)
; #pragma unroll
;                     for (int bj = 0; bj < 2; ++bj) { const int m = 2 * mp + mm; const size_t off = (size_t)(row0 + ai * HALF + m * 16) * 2048 + col0 + bj * HALF;
;                         const f32x4 v0 = b0[mm][bj] + acc[ai][bj][m][0], v1 = b1[mm][bj] + acc[ai][bj][m][1];
;                         if (OUT_BF) { u32x4 w; w.x = cvtpk(v0[0], v0[1]); w.y = cvtpk(v0[2], v0[3]); w.z = cvtpk(v1[0], v1[1]); w.w = cvtpk(v1[2], v1[3]); *(u32x4*)((bf16*)out + off) = w; }
;                         else { *(f32x4*)((float*)out + off) = v0; *(f32x4*)((float*)out + off + 4) = v1; } }
	v_lshlrev_b32_e32 v96, 16, v100
	v_and_b32_e32 v97, 0xffff0000, v100
	v_lshlrev_b32_e32 v98, 16, v101
	v_and_b32_e32 v99, 0xffff0000, v101
	s_waitcnt vmcnt(1)
	v_lshlrev_b32_e32 v162, 16, v114
	v_and_b32_e32 v163, 0xffff0000, v114
	v_lshlrev_b32_e32 v100, 16, v102
	v_and_b32_e32 v101, 0xffff0000, v102
	v_lshlrev_b32_e32 v102, 16, v103
	v_and_b32_e32 v103, 0xffff0000, v103
	v_lshlrev_b32_e32 v124, 16, v104
	v_and_b32_e32 v125, 0xffff0000, v104
	v_lshlrev_b32_e32 v150, 16, v108
	v_and_b32_e32 v151, 0xffff0000, v108
	v_lshlrev_b32_e32 v114, 16, v115
	v_and_b32_e32 v115, 0xffff0000, v115
	v_pk_add_f32 v[94:95], v[94:95], v[98:99]
	v_pk_add_f32 v[92:93], v[92:93], v[96:97]
	v_pk_add_f32 v[98:99], v[64:65], v[162:163]
	v_cvt_pk_bf16_f32 v64, v92, v93
	v_lshlrev_b32_e32 v104, 16, v105
	v_and_b32_e32 v105, 0xffff0000, v105
	v_lshlrev_b32_e32 v126, 16, v106
	v_and_b32_e32 v127, 0xffff0000, v106
	v_lshlrev_b32_e32 v106, 16, v107
	v_and_b32_e32 v107, 0xffff0000, v107
	v_lshlrev_b32_e32 v158, 16, v110
	v_and_b32_e32 v159, 0xffff0000, v110
	v_pk_add_f32 v[90:91], v[90:91], v[102:103]
	v_pk_add_f32 v[88:89], v[88:89], v[100:101]
	v_pk_add_f32 v[76:77], v[76:77], v[124:125]
	v_pk_add_f32 v[84:85], v[84:85], v[150:151]
	v_pk_add_f32 v[96:97], v[66:67], v[114:115]
	v_cvt_pk_bf16_f32 v65, v94, v95
	v_cvt_pk_bf16_f32 v66, v88, v89
	v_cvt_pk_bf16_f32 v67, v90, v91
	global_store_dwordx4 v[120:121], v[64:67], off
	v_lshlrev_b32_e32 v108, 16, v109
	v_and_b32_e32 v109, 0xffff0000, v109
	v_cvt_pk_bf16_f32 v64, v76, v77
	v_lshlrev_b32_e32 v110, 16, v111
	v_and_b32_e32 v111, 0xffff0000, v111
	v_lshlrev_b32_e32 v160, 16, v112
	v_and_b32_e32 v161, 0xffff0000, v112
	v_lshlrev_b32_e32 v112, 16, v113
	v_and_b32_e32 v113, 0xffff0000, v113
	v_pk_add_f32 v[78:79], v[78:79], v[104:105]
	v_pk_add_f32 v[74:75], v[74:75], v[106:107]
	v_pk_add_f32 v[72:73], v[72:73], v[126:127]
	v_pk_add_f32 v[80:81], v[80:81], v[158:159]
	v_cvt_pk_bf16_f32 v65, v78, v79
	v_cvt_pk_bf16_f32 v66, v72, v73
	v_cvt_pk_bf16_f32 v67, v74, v75
	global_store_dwordx4 v[120:121], v[64:67], off offset:256
	v_pk_add_f32 v[86:87], v[86:87], v[108:109]
	v_pk_add_f32 v[82:83], v[82:83], v[110:111]
	v_cvt_pk_bf16_f32 v64, v84, v85
	v_lshl_add_u64 v[84:85], v[148:149], 0, s[12:13]
	v_pk_add_f32 v[70:71], v[70:71], v[112:113]
	v_pk_add_f32 v[68:69], v[68:69], v[160:161]
	v_cvt_pk_bf16_f32 v65, v86, v87
	v_cvt_pk_bf16_f32 v66, v80, v81
	v_cvt_pk_bf16_f32 v67, v82, v83
	v_lshl_add_u64 v[80:81], v[146:147], 0, v[84:85]
	global_store_dwordx4 v[116:117], v[64:67], off
	v_lshl_add_u64 v[88:89], s[4:5], 0, v[118:119]
	v_lshl_add_u64 v[88:89], v[88:89], 0, v[144:145]
	v_cvt_pk_bf16_f32 v64, v68, v69
	v_cvt_pk_bf16_f32 v65, v70, v71
	v_cvt_pk_bf16_f32 v66, v98, v99
	v_cvt_pk_bf16_f32 v67, v96, v97
	global_load_dwordx4 v[68:71], v[122:123], off
	global_load_dwordx4 v[72:75], v[122:123], off offset:256
	global_load_dwordx4 v[76:79], v[80:81], off
	s_nop 0
	global_load_dwordx4 v[80:83], v[80:81], off offset:256
	v_lshl_add_u64 v[86:87], v[148:149], 0, s[14:15]
	global_store_dwordx4 v[116:117], v[64:67], off offset:256
	v_lshl_add_u64 v[84:85], s[4:5], 0, v[84:85]
	v_lshl_add_u64 v[90:91], v[146:147], 0, v[86:87]
	v_lshl_add_u64 v[84:85], v[84:85], 0, v[144:145]
	s_waitcnt vmcnt(4)
	v_lshlrev_b32_e32 v64, 16, v68
	v_and_b32_e32 v65, 0xffff0000, v68
	v_lshlrev_b32_e32 v66, 16, v69
	v_and_b32_e32 v67, 0xffff0000, v69
	s_waitcnt vmcnt(1)
;     __device__ __forceinline__ void operator()(const f32x4 (&acc)[2][2][4][2], const Unit& u, int wr, int wc, int fr, int fq) const {
;     ...
;             for (int mp = 0; mp < 2; ++mp) {
;                 f32x4 b0[2][2], b1[2][2];
; #pragma unroll
;                 for (int mm = 0; mm < 2; ++mm)
; #pragma unroll
;                     for (int bj = 0; bj < 2; ++bj) { const size_t off = (size_t)(row0 + ai * HALF + (2 * mp + mm) * 16) * 2048 + col0 + bj * HALF;
;                         if (BASE_BF) { const u32x4 w = *(const u32x4*)((const bf16*)base + off);
;                             b0[mm][bj] = (f32x4){bflo(w.x), bfhi(w.x), bflo(w.y), bfhi(w.y)}; b1[mm][bj] = (f32x4){bflo(w.z), bfhi(w.z), bflo(w.w), bfhi(w.w)}; }
;                         else { b0[mm][bj] = __builtin_nontemporal_load((const f32x4*)((const float*)base + off)); b1[mm][bj] = __builtin_nontemporal_load((const f32x4*)((const float*)base + off + 4)); } }
; #pragma unroll
;                 for (int mm = 0; mm < 2; ++mm)
; #pragma unroll
;                     for (int bj = 0; bj < 2; ++bj) { const int m = 2 * mp + mm; const size_t off = (size_t)(row0 + ai * HALF + m * 16) * 2048 + col0 + bj * HALF;
;                         const f32x4 v0 = b0[mm][bj] + acc[ai][bj][m][0], v1 = b1[mm][bj] + acc[ai][bj][m][1];
;                         if (OUT_BF) { u32x4 w; w.x = cvtpk(v0[0], v0[1]); w.y = cvtpk(v0[2], v0[3]); w.z = cvtpk(v1[0], v1[1]); w.w = cvtpk(v1[2], v1[3]); *(u32x4*)((bf16*)out + off) = w; }
;                         else { *(f32x4*)((float*)out + off) = v0; *(f32x4*)((float*)out + off + 4) = v1; } }
; template <class Epi, class Sched, bool ALIGN_EPI = false, bool SP2 = false>
; __device__ __forceinline__ void gemm_phase(PG8_LAS unsigned char* lds, const Gemm g, const Sched& S, const Epi& E, const int wv0) {
;     ...
;         if constexpr (epi_keeps_acc<Epi>::value) { E.mid(acc, cur, wr, wc, fr, fq); } else if constexpr (!Epi::AFTER_DRAIN) { E(acc, cur, wr, wc, fr, fq); }
;         if (!has_next) break;
;         if constexpr (!epi_keeps_acc<Epi>::value) {
; #pragma unroll
;         for (int a = 0; a < 2; ++a)
; #pragma unroll
;             for (int b = 0; b < 2; ++b)
; #pragma unroll
;                 for (int m = 0; m < 4; ++m)
; #pragma unroll
;                     for (int n = 0; n < 2; ++n) acc[a][b][m][n] = (f32x4){0.f, 0.f, 0.f, 0.f};
;         }
;         cur = nxt; cA = nA; cB = nB; ++ui;
	v_lshlrev_b32_e32 v102, 16, v82
	v_and_b32_e32 v103, 0xffff0000, v82
	v_lshlrev_b32_e32 v68, 16, v70
	v_and_b32_e32 v69, 0xffff0000, v70
	v_lshlrev_b32_e32 v70, 16, v71
	v_and_b32_e32 v71, 0xffff0000, v71
	v_lshlrev_b32_e32 v92, 16, v72
	v_and_b32_e32 v93, 0xffff0000, v72
	v_lshlrev_b32_e32 v96, 16, v76
	v_and_b32_e32 v97, 0xffff0000, v76
	v_lshlrev_b32_e32 v82, 16, v83
	v_and_b32_e32 v83, 0xffff0000, v83
	v_pk_add_f32 v[62:63], v[62:63], v[66:67]
	v_pk_add_f32 v[60:61], v[60:61], v[64:65]
	v_pk_add_f32 v[66:67], v[32:33], v[102:103]
	v_cvt_pk_bf16_f32 v32, v60, v61
	v_lshlrev_b32_e32 v72, 16, v73
	v_and_b32_e32 v73, 0xffff0000, v73
	v_lshlrev_b32_e32 v94, 16, v74
	v_and_b32_e32 v95, 0xffff0000, v74
	v_lshlrev_b32_e32 v74, 16, v75
	v_and_b32_e32 v75, 0xffff0000, v75
	v_lshlrev_b32_e32 v98, 16, v78
	v_and_b32_e32 v99, 0xffff0000, v78
	v_pk_add_f32 v[58:59], v[58:59], v[70:71]
	v_pk_add_f32 v[56:57], v[56:57], v[68:69]
	v_pk_add_f32 v[44:45], v[44:45], v[92:93]
	v_pk_add_f32 v[52:53], v[52:53], v[96:97]
	v_pk_add_f32 v[64:65], v[34:35], v[82:83]
	v_cvt_pk_bf16_f32 v33, v62, v63
	v_cvt_pk_bf16_f32 v34, v56, v57
	v_cvt_pk_bf16_f32 v35, v58, v59
	global_store_dwordx4 v[88:89], v[32:35], off
	v_lshlrev_b32_e32 v76, 16, v77
	v_and_b32_e32 v77, 0xffff0000, v77
	v_cvt_pk_bf16_f32 v32, v44, v45
	v_lshlrev_b32_e32 v78, 16, v79
	v_and_b32_e32 v79, 0xffff0000, v79
	v_lshlrev_b32_e32 v100, 16, v80
	v_and_b32_e32 v101, 0xffff0000, v80
	v_lshlrev_b32_e32 v80, 16, v81
	v_and_b32_e32 v81, 0xffff0000, v81
	v_pk_add_f32 v[46:47], v[46:47], v[72:73]
	v_pk_add_f32 v[42:43], v[42:43], v[74:75]
	v_pk_add_f32 v[40:41], v[40:41], v[94:95]
	v_pk_add_f32 v[48:49], v[48:49], v[98:99]
	v_cvt_pk_bf16_f32 v33, v46, v47
	v_cvt_pk_bf16_f32 v34, v40, v41
	v_cvt_pk_bf16_f32 v35, v42, v43
	global_store_dwordx4 v[88:89], v[32:35], off offset:256
	v_pk_add_f32 v[54:55], v[54:55], v[76:77]
	v_pk_add_f32 v[50:51], v[50:51], v[78:79]
	v_cvt_pk_bf16_f32 v32, v52, v53
	v_lshl_add_u64 v[52:53], v[148:149], 0, s[16:17]
	v_pk_add_f32 v[38:39], v[38:39], v[80:81]
	v_pk_add_f32 v[36:37], v[36:37], v[100:101]
	v_cvt_pk_bf16_f32 v33, v54, v55
	v_cvt_pk_bf16_f32 v34, v48, v49
	v_cvt_pk_bf16_f32 v35, v50, v51
	v_lshl_add_u64 v[48:49], v[146:147], 0, v[52:53]
	global_store_dwordx4 v[84:85], v[32:35], off
	v_lshl_add_u64 v[54:55], s[4:5], 0, v[86:87]
	v_lshl_add_u64 v[54:55], v[54:55], 0, v[144:145]
	v_cvt_pk_bf16_f32 v32, v36, v37
	v_cvt_pk_bf16_f32 v33, v38, v39
	v_cvt_pk_bf16_f32 v34, v66, v67
	v_cvt_pk_bf16_f32 v35, v64, v65
	global_load_dwordx4 v[36:39], v[90:91], off
	global_load_dwordx4 v[40:43], v[90:91], off offset:256
	global_load_dwordx4 v[44:47], v[48:49], off
	s_nop 0
	global_load_dwordx4 v[48:51], v[48:49], off offset:256
	v_lshl_add_u64 v[52:53], s[4:5], 0, v[52:53]
	global_store_dwordx4 v[84:85], v[32:35], off offset:256
	v_lshl_add_u64 v[52:53], v[52:53], 0, v[144:145]
	s_waitcnt vmcnt(3)
	v_lshlrev_b32_e32 v56, 16, v40
	v_lshlrev_b32_e32 v32, 16, v36
	v_and_b32_e32 v33, 0xffff0000, v36
	v_lshlrev_b32_e32 v34, 16, v37
	v_and_b32_e32 v35, 0xffff0000, v37
	v_lshlrev_b32_e32 v36, 16, v38
	v_and_b32_e32 v37, 0xffff0000, v38
	v_lshlrev_b32_e32 v38, 16, v39
	v_and_b32_e32 v39, 0xffff0000, v39
	s_waitcnt vmcnt(1)
	v_lshlrev_b32_e32 v66, 16, v50
	v_and_b32_e32 v67, 0xffff0000, v50
	v_lshlrev_b32_e32 v50, 16, v51
	v_and_b32_e32 v51, 0xffff0000, v51
	v_and_b32_e32 v57, 0xffff0000, v40
	v_lshlrev_b32_e32 v40, 16, v41
	v_and_b32_e32 v41, 0xffff0000, v41
	v_lshlrev_b32_e32 v58, 16, v42
	v_and_b32_e32 v59, 0xffff0000, v42
	v_lshlrev_b32_e32 v42, 16, v43
	v_and_b32_e32 v43, 0xffff0000, v43
	v_pk_add_f32 v[30:31], v[30:31], v[34:35]
	v_pk_add_f32 v[28:29], v[28:29], v[32:33]
	v_pk_add_f32 v[26:27], v[26:27], v[38:39]
	v_pk_add_f32 v[24:25], v[24:25], v[36:37]
	v_pk_add_f32 v[32:33], v[2:3], v[50:51]
	v_pk_add_f32 v[34:35], v[0:1], v[66:67]
	v_cvt_pk_bf16_f32 v0, v28, v29
	v_cvt_pk_bf16_f32 v1, v30, v31
	v_cvt_pk_bf16_f32 v2, v24, v25
	v_cvt_pk_bf16_f32 v3, v26, v27
	v_lshlrev_b32_e32 v60, 16, v44
	v_and_b32_e32 v61, 0xffff0000, v44
	v_lshlrev_b32_e32 v44, 16, v45
	v_and_b32_e32 v45, 0xffff0000, v45
	v_lshlrev_b32_e32 v62, 16, v46
	v_and_b32_e32 v63, 0xffff0000, v46
	v_lshlrev_b32_e32 v46, 16, v47
	v_and_b32_e32 v47, 0xffff0000, v47
	v_pk_add_f32 v[14:15], v[14:15], v[40:41]
	v_pk_add_f32 v[12:13], v[12:13], v[56:57]
	v_pk_add_f32 v[10:11], v[10:11], v[42:43]
	v_pk_add_f32 v[8:9], v[8:9], v[58:59]
	global_store_dwordx4 v[54:55], v[0:3], off
	v_lshlrev_b32_e32 v64, 16, v48
	v_and_b32_e32 v65, 0xffff0000, v48
	v_cvt_pk_bf16_f32 v0, v12, v13
	v_cvt_pk_bf16_f32 v1, v14, v15
	v_cvt_pk_bf16_f32 v2, v8, v9
	v_cvt_pk_bf16_f32 v3, v10, v11
	v_lshlrev_b32_e32 v48, 16, v49
	v_and_b32_e32 v49, 0xffff0000, v49
	v_pk_add_f32 v[22:23], v[22:23], v[44:45]
	v_pk_add_f32 v[20:21], v[20:21], v[60:61]
	v_pk_add_f32 v[18:19], v[18:19], v[46:47]
	v_pk_add_f32 v[16:17], v[16:17], v[62:63]
	global_store_dwordx4 v[54:55], v[0:3], off offset:256
	v_pk_add_f32 v[6:7], v[6:7], v[48:49]
	v_pk_add_f32 v[4:5], v[4:5], v[64:65]
	v_cvt_pk_bf16_f32 v0, v20, v21
	v_cvt_pk_bf16_f32 v1, v22, v23
	v_cvt_pk_bf16_f32 v2, v16, v17
	v_cvt_pk_bf16_f32 v3, v18, v19
	global_store_dwordx4 v[52:53], v[0:3], off
	s_nop 1
	v_cvt_pk_bf16_f32 v0, v4, v5
	v_cvt_pk_bf16_f32 v1, v6, v7
	v_cvt_pk_bf16_f32 v2, v34, v35
	v_cvt_pk_bf16_f32 v3, v32, v33
	global_store_dwordx4 v[52:53], v[0:3], off offset:256
	s_cbranch_vccnz .LBB0_859
	s_andn2_b64 vcc, exec, s[2:3]
	s_cbranch_vccnz .LBB0_858
	s_barrier
	s_branch .LBB0_858

; __device__ __forceinline__ unsigned cvtpk(float lo, float hi) { unsigned r; asm volatile("v_cvt_pk_bf16_f32 %0, %1, %2" : "=v"(r) : "v"(lo), "v"(hi)); return r; }
;     __device__ __forceinline__ float* out() const { return (float*)(__attribute__((address_space(1))) float*)get(20); }
;     __device__ __forceinline__ void operator()(const f32x4 (&acc)[2][2][4][2], const Unit& u, int wr, int wc, int fr, int fq) const {
;         const int row0 = u.pm * BM + wr * 64 + fr, col0 = u.pn * BM + wc * 32 + 8 * fq;
; #pragma unroll
;         for (int ai = 0; ai < 2; ++ai)
; #pragma unroll
;             for (int mp = 0; mp < 2; ++mp) {
;                 f32x4 b0[2][2], b1[2][2];
; #pragma unroll
;                 for (int mm = 0; mm < 2; ++mm)
; #pragma unroll
;                     for (int bj = 0; bj < 2; ++bj) { const size_t off = (size_t)(row0 + ai * HALF + (2 * mp + mm) * 16) * 2048 + col0 + bj * HALF;
;                         if (BASE_BF) { const u32x4 w = *(const u32x4*)((const bf16*)base + off);
;                             b0[mm][bj] = (f32x4){bflo(w.x), bfhi(w.x), bflo(w.y), bfhi(w.y)}; b1[mm][bj] = (f32x4){bflo(w.z), bfhi(w.z), bflo(w.w), bfhi(w.w)}; }
;                         else { b0[mm][bj] = __builtin_nontemporal_load((const f32x4*)((const float*)base + off)); b1[mm][bj] = __builtin_nontemporal_load((const f32x4*)((const float*)base + off + 4)); } }
; #pragma unroll
;                 for (int mm = 0; mm < 2; ++mm)
; #pragma unroll
;                     for (int bj = 0; bj < 2; ++bj) { const int m = 2 * mp + mm; const size_t off = (size_t)(row0 + ai * HALF + m * 16) * 2048 + col0 + bj * HALF;
;                         const f32x4 v0 = b0[mm][bj] + acc[ai][bj][m][0], v1 = b1[mm][bj] + acc[ai][bj][m][1];
;                         if (OUT_BF) { u32x4 w; w.x = cvtpk(v0[0], v0[1]); w.y = cvtpk(v0[2], v0[3]); w.z = cvtpk(v1[0], v1[1]); w.w = cvtpk(v1[2], v1[3]); *(u32x4*)((bf16*)out + off) = w; }
;                         else { *(f32x4*)((float*)out + off) = v0; *(f32x4*)((float*)out + off + 4) = v1; } }
;             }
;     }
.LBB0_1611:
	v_lshl_add_u32 v150, s26, 8, v152
	v_lshl_or_b32 v144, s55, 8, v154
	v_ashrrev_i32_e32 v145, 31, v144
	v_or_b32_e32 v166, 16, v150
	v_lshlrev_b64 v[144:145], 1, v[144:145]
	v_ashrrev_i32_e32 v151, 31, v150
	v_ashrrev_i32_e32 v167, 31, v166
	v_lshl_add_u64 v[146:147], s[6:7], 0, v[144:145]
	v_lshlrev_b64 v[148:149], 12, v[150:151]
	v_lshlrev_b64 v[174:175], 12, v[166:167]
	v_lshl_add_u64 v[162:163], v[146:147], 0, v[148:149]
	v_lshl_add_u64 v[170:171], v[146:147], 0, v[174:175]
	s_mov_b32 s81, 0
	s_mov_b32 s80, 0x20000
	v_lshl_add_u64 v[248:249], v[162:163], 0, s[80:81]
	global_load_dwordx4 v[198:201], v[248:249], off
	global_load_dwordx4 v[206:209], v[248:249], off offset:256
	s_mov_b32 s80, 0x30000
	v_lshl_add_u64 v[248:249], v[162:163], 0, s[80:81]
	global_load_dwordx4 v[210:213], v[248:249], off
	global_load_dwordx4 v[214:217], v[248:249], off offset:256
	s_mov_b32 s80, 0x80000
	v_lshl_add_u64 v[248:249], v[162:163], 0, s[80:81]
	global_load_dwordx4 v[218:221], v[248:249], off
	global_load_dwordx4 v[222:225], v[248:249], off offset:256
	s_mov_b32 s80, 0x90000
	v_lshl_add_u64 v[248:249], v[162:163], 0, s[80:81]
	global_load_dwordx4 v[226:229], v[248:249], off
	global_load_dwordx4 v[232:235], v[248:249], off offset:256
	s_mov_b32 s80, 0xa0000
	v_lshl_add_u64 v[248:249], v[162:163], 0, s[80:81]
	global_load_dwordx4 v[236:239], v[248:249], off
	global_load_dwordx4 v[240:243], v[248:249], off offset:256
	s_mov_b32 s80, 0xb0000
	v_lshl_add_u64 v[248:249], v[162:163], 0, s[80:81]
	global_load_dwordx4 v[244:247], v[248:249], off
	global_load_dwordx4 v[250:253], v[248:249], off offset:256
	global_load_dwordx4 v[158:161], v[162:163], off
	s_nop 0
	global_load_dwordx4 v[162:165], v[162:163], off offset:256
	s_nop 0
	global_load_dwordx4 v[166:169], v[170:171], off
	s_nop 0
	global_load_dwordx4 v[170:173], v[170:171], off offset:256
	v_lshl_add_u64 v[178:179], s[6:7], 0, v[148:149]
	v_lshl_add_u64 v[178:179], v[178:179], 0, v[144:145]
	v_or_b32_e32 v176, 32, v150
	v_ashrrev_i32_e32 v177, 31, v176
	v_lshlrev_b64 v[176:177], 12, v[176:177]
	v_lshl_add_u64 v[174:175], s[6:7], 0, v[174:175]
	v_lshl_add_u64 v[180:181], v[146:147], 0, v[176:177]
	v_lshl_add_u64 v[174:175], v[174:175], 0, v[144:145]
	s_andn2_b64 vcc, exec, s[0:1]
	s_mov_b64 s[0:1], -1
	s_waitcnt vmcnt(0)
	v_lshlrev_b32_e32 v182, 16, v158
	v_and_b32_e32 v183, 0xffff0000, v158
	v_lshlrev_b32_e32 v184, 16, v160
	v_and_b32_e32 v185, 0xffff0000, v160
	v_lshlrev_b32_e32 v160, 16, v161
	v_and_b32_e32 v161, 0xffff0000, v161
	v_lshlrev_b32_e32 v186, 16, v162
	v_and_b32_e32 v187, 0xffff0000, v162
	v_lshlrev_b32_e32 v196, 16, v172
	v_and_b32_e32 v197, 0xffff0000, v172
	v_lshlrev_b32_e32 v158, 16, v159
	v_and_b32_e32 v159, 0xffff0000, v159
	v_lshlrev_b32_e32 v172, 16, v173
	v_and_b32_e32 v173, 0xffff0000, v173
	v_pk_add_f32 v[124:125], v[124:125], v[182:183]
	v_pk_add_f32 v[122:123], v[122:123], v[160:161]
	v_pk_add_f32 v[108:109], v[108:109], v[186:187]
	v_pk_add_f32 v[160:161], v[96:97], v[196:197]
	v_cvt_pk_bf16_f32 v96, v124, v125
	v_lshlrev_b32_e32 v190, 16, v166
	v_and_b32_e32 v191, 0xffff0000, v166
	v_pk_add_f32 v[126:127], v[126:127], v[158:159]
	v_pk_add_f32 v[120:121], v[120:121], v[184:185]
	v_pk_add_f32 v[158:159], v[98:99], v[172:173]
	v_cvt_pk_bf16_f32 v97, v126, v127
	v_cvt_pk_bf16_f32 v98, v120, v121
	v_cvt_pk_bf16_f32 v99, v122, v123
	global_store_dwordx4 v[178:179], v[96:99], off
	v_lshlrev_b32_e32 v162, 16, v163
	v_and_b32_e32 v163, 0xffff0000, v163
	v_cvt_pk_bf16_f32 v96, v108, v109
	v_or_b32_e32 v108, 48, v150
	v_lshlrev_b32_e32 v188, 16, v164
	v_and_b32_e32 v189, 0xffff0000, v164
	v_lshlrev_b32_e32 v164, 16, v165
	v_and_b32_e32 v165, 0xffff0000, v165
	v_lshlrev_b32_e32 v192, 16, v168
	v_and_b32_e32 v193, 0xffff0000, v168
	v_pk_add_f32 v[116:117], v[116:117], v[190:191]
	v_ashrrev_i32_e32 v109, 31, v108
	v_lshlrev_b32_e32 v166, 16, v167
	v_and_b32_e32 v167, 0xffff0000, v167
	v_lshlrev_b32_e32 v168, 16, v169
	v_and_b32_e32 v169, 0xffff0000, v169
	v_lshlrev_b32_e32 v194, 16, v170
	v_and_b32_e32 v195, 0xffff0000, v170
	v_lshlrev_b32_e32 v170, 16, v171
	v_and_b32_e32 v171, 0xffff0000, v171
	v_pk_add_f32 v[110:111], v[110:111], v[162:163]
	v_pk_add_f32 v[106:107], v[106:107], v[164:165]
	v_pk_add_f32 v[104:105], v[104:105], v[188:189]
	v_pk_add_f32 v[112:113], v[112:113], v[192:193]
	v_cvt_pk_bf16_f32 v97, v110, v111
	v_cvt_pk_bf16_f32 v98, v104, v105
	v_cvt_pk_bf16_f32 v99, v106, v107
	global_store_dwordx4 v[178:179], v[96:99], off offset:256
	v_pk_add_f32 v[118:119], v[118:119], v[166:167]
	v_pk_add_f32 v[114:115], v[114:115], v[168:169]
	v_cvt_pk_bf16_f32 v96, v116, v117
	v_lshlrev_b64 v[116:117], 12, v[108:109]
	v_pk_add_f32 v[102:103], v[102:103], v[170:171]
	v_pk_add_f32 v[100:101], v[100:101], v[194:195]
	v_cvt_pk_bf16_f32 v97, v118, v119
	v_cvt_pk_bf16_f32 v98, v112, v113
	v_cvt_pk_bf16_f32 v99, v114, v115
	v_lshl_add_u64 v[112:113], v[146:147], 0, v[116:117]
	global_store_dwordx4 v[174:175], v[96:99], off
	v_lshl_add_u64 v[120:121], s[6:7], 0, v[176:177]
	v_lshl_add_u64 v[120:121], v[120:121], 0, v[144:145]
	v_cvt_pk_bf16_f32 v96, v100, v101
	v_cvt_pk_bf16_f32 v97, v102, v103
	v_cvt_pk_bf16_f32 v98, v160, v161
	v_cvt_pk_bf16_f32 v99, v158, v159
	global_load_dwordx4 v[100:103], v[180:181], off
	global_load_dwordx4 v[104:107], v[180:181], off offset:256
	global_load_dwordx4 v[108:111], v[112:113], off
	s_nop 0
	global_load_dwordx4 v[112:115], v[112:113], off offset:256
	v_lshl_add_u64 v[118:119], v[148:149], 0, s[2:3]
	global_store_dwordx4 v[174:175], v[96:99], off offset:256
	v_lshl_add_u64 v[116:117], s[6:7], 0, v[116:117]
	v_lshl_add_u64 v[122:123], v[146:147], 0, v[118:119]
	v_lshl_add_u64 v[116:117], v[116:117], 0, v[144:145]
	s_waitcnt vmcnt(4)
; __device__ __forceinline__ unsigned cvtpk(float lo, float hi) { unsigned r; asm volatile("v_cvt_pk_bf16_f32 %0, %1, %2" : "=v"(r) : "v"(lo), "v"(hi)); return r; }
;     __device__ __forceinline__ float* out() const { return (float*)(__attribute__((address_space(1))) float*)get(20); }
;     __device__ __forceinline__ void operator()(const f32x4 (&acc)[2][2][4][2], const Unit& u, int wr, int wc, int fr, int fq) const {
;     ...
;             for (int mp = 0; mp < 2; ++mp) {
;                 f32x4 b0[2][2], b1[2][2];
; #pragma unroll
;                 for (int mm = 0; mm < 2; ++mm)
; #pragma unroll
;                     for (int bj = 0; bj < 2; ++bj) { const size_t off = (size_t)(row0 + ai * HALF + (2 * mp + mm) * 16) * 2048 + col0 + bj * HALF;
;                         if (BASE_BF) { const u32x4 w = *(const u32x4*)((const bf16*)base + off);
;                             b0[mm][bj] = (f32x4){bflo(w.x), bfhi(w.x), bflo(w.y), bfhi(w.y)}; b1[mm][bj] = (f32x4){bflo(w.z), bfhi(w.z), bflo(w.w), bfhi(w.w)}; }
;                         else { b0[mm][bj] = __builtin_nontemporal_load((const f32x4*)((const float*)base + off)); b1[mm][bj] = __builtin_nontemporal_load((const f32x4*)((const float*)base + off + 4)); } }
; #pragma unroll
;                 for (int mm = 0; mm < 2; ++mm)
; #pragma unroll
;                     for (int bj = 0; bj < 2; ++bj) { const int m = 2 * mp + mm; const size_t off = (size_t)(row0 + ai * HALF + m * 16) * 2048 + col0 + bj * HALF;
;                         const f32x4 v0 = b0[mm][bj] + acc[ai][bj][m][0], v1 = b1[mm][bj] + acc[ai][bj][m][1];
;                         if (OUT_BF) { u32x4 w; w.x = cvtpk(v0[0], v0[1]); w.y = cvtpk(v0[2], v0[3]); w.z = cvtpk(v1[0], v1[1]); w.w = cvtpk(v1[2], v1[3]); *(u32x4*)((bf16*)out + off) = w; }
;                         else { *(f32x4*)((float*)out + off) = v0; *(f32x4*)((float*)out + off + 4) = v1; } }
	v_lshlrev_b32_e32 v96, 16, v100
	v_and_b32_e32 v97, 0xffff0000, v100
	v_lshlrev_b32_e32 v98, 16, v101
	v_and_b32_e32 v99, 0xffff0000, v101
	s_waitcnt vmcnt(1)
	v_lshlrev_b32_e32 v162, 16, v114
	v_and_b32_e32 v163, 0xffff0000, v114
	v_lshlrev_b32_e32 v100, 16, v102
	v_and_b32_e32 v101, 0xffff0000, v102
	v_lshlrev_b32_e32 v102, 16, v103
	v_and_b32_e32 v103, 0xffff0000, v103
	v_lshlrev_b32_e32 v124, 16, v104
	v_and_b32_e32 v125, 0xffff0000, v104
	v_lshlrev_b32_e32 v150, 16, v108
	v_and_b32_e32 v151, 0xffff0000, v108
	v_lshlrev_b32_e32 v114, 16, v115
	v_and_b32_e32 v115, 0xffff0000, v115
	v_pk_add_f32 v[94:95], v[94:95], v[98:99]
	v_pk_add_f32 v[92:93], v[92:93], v[96:97]
	v_pk_add_f32 v[98:99], v[64:65], v[162:163]
	v_cvt_pk_bf16_f32 v64, v92, v93
	v_lshlrev_b32_e32 v104, 16, v105
	v_and_b32_e32 v105, 0xffff0000, v105
	v_lshlrev_b32_e32 v126, 16, v106
	v_and_b32_e32 v127, 0xffff0000, v106
	v_lshlrev_b32_e32 v106, 16, v107
	v_and_b32_e32 v107, 0xffff0000, v107
	v_lshlrev_b32_e32 v158, 16, v110
	v_and_b32_e32 v159, 0xffff0000, v110
	v_pk_add_f32 v[90:91], v[90:91], v[102:103]
	v_pk_add_f32 v[88:89], v[88:89], v[100:101]
	v_pk_add_f32 v[76:77], v[76:77], v[124:125]
	v_pk_add_f32 v[84:85], v[84:85], v[150:151]
	v_pk_add_f32 v[96:97], v[66:67], v[114:115]
	v_cvt_pk_bf16_f32 v65, v94, v95
	v_cvt_pk_bf16_f32 v66, v88, v89
	v_cvt_pk_bf16_f32 v67, v90, v91
	global_store_dwordx4 v[120:121], v[64:67], off
	v_lshlrev_b32_e32 v108, 16, v109
	v_and_b32_e32 v109, 0xffff0000, v109
	v_cvt_pk_bf16_f32 v64, v76, v77
	v_lshlrev_b32_e32 v110, 16, v111
	v_and_b32_e32 v111, 0xffff0000, v111
	v_lshlrev_b32_e32 v160, 16, v112
	v_and_b32_e32 v161, 0xffff0000, v112
	v_lshlrev_b32_e32 v112, 16, v113
	v_and_b32_e32 v113, 0xffff0000, v113
	v_pk_add_f32 v[78:79], v[78:79], v[104:105]
	v_pk_add_f32 v[74:75], v[74:75], v[106:107]
	v_pk_add_f32 v[72:73], v[72:73], v[126:127]
	v_pk_add_f32 v[80:81], v[80:81], v[158:159]
	v_cvt_pk_bf16_f32 v65, v78, v79
	v_cvt_pk_bf16_f32 v66, v72, v73
	v_cvt_pk_bf16_f32 v67, v74, v75
	global_store_dwordx4 v[120:121], v[64:67], off offset:256
	v_pk_add_f32 v[86:87], v[86:87], v[108:109]
	v_pk_add_f32 v[82:83], v[82:83], v[110:111]
	v_cvt_pk_bf16_f32 v64, v84, v85
	v_lshl_add_u64 v[84:85], v[148:149], 0, s[12:13]
	v_pk_add_f32 v[70:71], v[70:71], v[112:113]
	v_pk_add_f32 v[68:69], v[68:69], v[160:161]
	v_cvt_pk_bf16_f32 v65, v86, v87
	v_cvt_pk_bf16_f32 v66, v80, v81
	v_cvt_pk_bf16_f32 v67, v82, v83
	v_lshl_add_u64 v[80:81], v[146:147], 0, v[84:85]
	global_store_dwordx4 v[116:117], v[64:67], off
	v_lshl_add_u64 v[88:89], s[6:7], 0, v[118:119]
	v_lshl_add_u64 v[88:89], v[88:89], 0, v[144:145]
	v_cvt_pk_bf16_f32 v64, v68, v69
	v_cvt_pk_bf16_f32 v65, v70, v71
	v_cvt_pk_bf16_f32 v66, v98, v99
	v_cvt_pk_bf16_f32 v67, v96, v97
	global_load_dwordx4 v[68:71], v[122:123], off
	global_load_dwordx4 v[72:75], v[122:123], off offset:256
	global_load_dwordx4 v[76:79], v[80:81], off
	s_nop 0
	global_load_dwordx4 v[80:83], v[80:81], off offset:256
	v_lshl_add_u64 v[86:87], v[148:149], 0, s[14:15]
	global_store_dwordx4 v[116:117], v[64:67], off offset:256
	v_lshl_add_u64 v[84:85], s[6:7], 0, v[84:85]
	v_lshl_add_u64 v[90:91], v[146:147], 0, v[86:87]
	v_lshl_add_u64 v[84:85], v[84:85], 0, v[144:145]
	s_waitcnt vmcnt(4)
	v_lshlrev_b32_e32 v64, 16, v68
	v_and_b32_e32 v65, 0xffff0000, v68
	v_lshlrev_b32_e32 v66, 16, v69
	v_and_b32_e32 v67, 0xffff0000, v69
	s_waitcnt vmcnt(1)
;     __device__ __forceinline__ void operator()(const f32x4 (&acc)[2][2][4][2], const Unit& u, int wr, int wc, int fr, int fq) const {
;     ...
;             for (int mp = 0; mp < 2; ++mp) {
;                 f32x4 b0[2][2], b1[2][2];
; #pragma unroll
;                 for (int mm = 0; mm < 2; ++mm)
; #pragma unroll
;                     for (int bj = 0; bj < 2; ++bj) { const size_t off = (size_t)(row0 + ai * HALF + (2 * mp + mm) * 16) * 2048 + col0 + bj * HALF;
;                         if (BASE_BF) { const u32x4 w = *(const u32x4*)((const bf16*)base + off);
;                             b0[mm][bj] = (f32x4){bflo(w.x), bfhi(w.x), bflo(w.y), bfhi(w.y)}; b1[mm][bj] = (f32x4){bflo(w.z), bfhi(w.z), bflo(w.w), bfhi(w.w)}; }
;                         else { b0[mm][bj] = __builtin_nontemporal_load((const f32x4*)((const float*)base + off)); b1[mm][bj] = __builtin_nontemporal_load((const f32x4*)((const float*)base + off + 4)); } }
; #pragma unroll
;                 for (int mm = 0; mm < 2; ++mm)
; #pragma unroll
;                     for (int bj = 0; bj < 2; ++bj) { const int m = 2 * mp + mm; const size_t off = (size_t)(row0 + ai * HALF + m * 16) * 2048 + col0 + bj * HALF;
;                         const f32x4 v0 = b0[mm][bj] + acc[ai][bj][m][0], v1 = b1[mm][bj] + acc[ai][bj][m][1];
;                         if (OUT_BF) { u32x4 w; w.x = cvtpk(v0[0], v0[1]); w.y = cvtpk(v0[2], v0[3]); w.z = cvtpk(v1[0], v1[1]); w.w = cvtpk(v1[2], v1[3]); *(u32x4*)((bf16*)out + off) = w; }
;                         else { *(f32x4*)((float*)out + off) = v0; *(f32x4*)((float*)out + off + 4) = v1; } }
; template <class Epi, class Sched, bool ALIGN_EPI = false, bool SP2 = false>
; __device__ __forceinline__ void gemm_phase(PG8_LAS unsigned char* lds, const Gemm g, const Sched& S, const Epi& E, const int wv0) {
;     ...
;         if constexpr (epi_keeps_acc<Epi>::value) { E.mid(acc, cur, wr, wc, fr, fq); } else if constexpr (!Epi::AFTER_DRAIN) { E(acc, cur, wr, wc, fr, fq); }
;         if (!has_next) break;
;         if constexpr (!epi_keeps_acc<Epi>::value) {
; #pragma unroll
;         for (int a = 0; a < 2; ++a)
; #pragma unroll
;             for (int b = 0; b < 2; ++b)
; #pragma unroll
;                 for (int m = 0; m < 4; ++m)
; #pragma unroll
;                     for (int n = 0; n < 2; ++n) acc[a][b][m][n] = (f32x4){0.f, 0.f, 0.f, 0.f};
;         }
;         cur = nxt; cA = nA; cB = nB; ++ui;
	v_lshlrev_b32_e32 v102, 16, v82
	v_and_b32_e32 v103, 0xffff0000, v82
	v_lshlrev_b32_e32 v68, 16, v70
	v_and_b32_e32 v69, 0xffff0000, v70
	v_lshlrev_b32_e32 v70, 16, v71
	v_and_b32_e32 v71, 0xffff0000, v71
	v_lshlrev_b32_e32 v92, 16, v72
	v_and_b32_e32 v93, 0xffff0000, v72
	v_lshlrev_b32_e32 v96, 16, v76
	v_and_b32_e32 v97, 0xffff0000, v76
	v_lshlrev_b32_e32 v82, 16, v83
	v_and_b32_e32 v83, 0xffff0000, v83
	v_pk_add_f32 v[62:63], v[62:63], v[66:67]
	v_pk_add_f32 v[60:61], v[60:61], v[64:65]
	v_pk_add_f32 v[66:67], v[32:33], v[102:103]
	v_cvt_pk_bf16_f32 v32, v60, v61
	v_lshlrev_b32_e32 v72, 16, v73
	v_and_b32_e32 v73, 0xffff0000, v73
	v_lshlrev_b32_e32 v94, 16, v74
	v_and_b32_e32 v95, 0xffff0000, v74
	v_lshlrev_b32_e32 v74, 16, v75
	v_and_b32_e32 v75, 0xffff0000, v75
	v_lshlrev_b32_e32 v98, 16, v78
	v_and_b32_e32 v99, 0xffff0000, v78
	v_pk_add_f32 v[58:59], v[58:59], v[70:71]
	v_pk_add_f32 v[56:57], v[56:57], v[68:69]
	v_pk_add_f32 v[44:45], v[44:45], v[92:93]
	v_pk_add_f32 v[52:53], v[52:53], v[96:97]
	v_pk_add_f32 v[64:65], v[34:35], v[82:83]
	v_cvt_pk_bf16_f32 v33, v62, v63
	v_cvt_pk_bf16_f32 v34, v56, v57
	v_cvt_pk_bf16_f32 v35, v58, v59
	global_store_dwordx4 v[88:89], v[32:35], off
	v_lshlrev_b32_e32 v76, 16, v77
	v_and_b32_e32 v77, 0xffff0000, v77
	v_cvt_pk_bf16_f32 v32, v44, v45
	v_lshlrev_b32_e32 v78, 16, v79
	v_and_b32_e32 v79, 0xffff0000, v79
	v_lshlrev_b32_e32 v100, 16, v80
	v_and_b32_e32 v101, 0xffff0000, v80
	v_lshlrev_b32_e32 v80, 16, v81
	v_and_b32_e32 v81, 0xffff0000, v81
	v_pk_add_f32 v[46:47], v[46:47], v[72:73]
	v_pk_add_f32 v[42:43], v[42:43], v[74:75]
	v_pk_add_f32 v[40:41], v[40:41], v[94:95]
	v_pk_add_f32 v[48:49], v[48:49], v[98:99]
	v_cvt_pk_bf16_f32 v33, v46, v47
	v_cvt_pk_bf16_f32 v34, v40, v41
	v_cvt_pk_bf16_f32 v35, v42, v43
	global_store_dwordx4 v[88:89], v[32:35], off offset:256
	v_pk_add_f32 v[54:55], v[54:55], v[76:77]
	v_pk_add_f32 v[50:51], v[50:51], v[78:79]
	v_cvt_pk_bf16_f32 v32, v52, v53
	v_lshl_add_u64 v[52:53], v[148:149], 0, s[16:17]
	v_pk_add_f32 v[38:39], v[38:39], v[80:81]
	v_pk_add_f32 v[36:37], v[36:37], v[100:101]
	v_cvt_pk_bf16_f32 v33, v54, v55
	v_cvt_pk_bf16_f32 v34, v48, v49
	v_cvt_pk_bf16_f32 v35, v50, v51
	v_lshl_add_u64 v[48:49], v[146:147], 0, v[52:53]
	global_store_dwordx4 v[84:85], v[32:35], off
	v_lshl_add_u64 v[54:55], s[6:7], 0, v[86:87]
	v_lshl_add_u64 v[54:55], v[54:55], 0, v[144:145]
	v_cvt_pk_bf16_f32 v32, v36, v37
	v_cvt_pk_bf16_f32 v33, v38, v39
	v_cvt_pk_bf16_f32 v34, v66, v67
	v_cvt_pk_bf16_f32 v35, v64, v65
	global_load_dwordx4 v[36:39], v[90:91], off
	global_load_dwordx4 v[40:43], v[90:91], off offset:256
	global_load_dwordx4 v[44:47], v[48:49], off
	s_nop 0
	global_load_dwordx4 v[48:51], v[48:49], off offset:256
	v_lshl_add_u64 v[52:53], s[6:7], 0, v[52:53]
	global_store_dwordx4 v[84:85], v[32:35], off offset:256
	v_lshl_add_u64 v[52:53], v[52:53], 0, v[144:145]
	s_waitcnt vmcnt(3)
	v_lshlrev_b32_e32 v56, 16, v40
	v_lshlrev_b32_e32 v32, 16, v36
	v_and_b32_e32 v33, 0xffff0000, v36
	v_lshlrev_b32_e32 v34, 16, v37
	v_and_b32_e32 v35, 0xffff0000, v37
	v_lshlrev_b32_e32 v36, 16, v38
	v_and_b32_e32 v37, 0xffff0000, v38
	v_lshlrev_b32_e32 v38, 16, v39
	v_and_b32_e32 v39, 0xffff0000, v39
	s_waitcnt vmcnt(1)
	v_lshlrev_b32_e32 v66, 16, v50
	v_and_b32_e32 v67, 0xffff0000, v50
	v_lshlrev_b32_e32 v50, 16, v51
	v_and_b32_e32 v51, 0xffff0000, v51
	v_and_b32_e32 v57, 0xffff0000, v40
	v_lshlrev_b32_e32 v40, 16, v41
	v_and_b32_e32 v41, 0xffff0000, v41
	v_lshlrev_b32_e32 v58, 16, v42
	v_and_b32_e32 v59, 0xffff0000, v42
	v_lshlrev_b32_e32 v42, 16, v43
	v_and_b32_e32 v43, 0xffff0000, v43
	v_pk_add_f32 v[30:31], v[30:31], v[34:35]
	v_pk_add_f32 v[28:29], v[28:29], v[32:33]
	v_pk_add_f32 v[26:27], v[26:27], v[38:39]
	v_pk_add_f32 v[24:25], v[24:25], v[36:37]
	v_pk_add_f32 v[32:33], v[2:3], v[50:51]
	v_pk_add_f32 v[34:35], v[0:1], v[66:67]
	v_cvt_pk_bf16_f32 v0, v28, v29
	v_cvt_pk_bf16_f32 v1, v30, v31
	v_cvt_pk_bf16_f32 v2, v24, v25
	v_cvt_pk_bf16_f32 v3, v26, v27
	v_lshlrev_b32_e32 v60, 16, v44
	v_and_b32_e32 v61, 0xffff0000, v44
	v_lshlrev_b32_e32 v44, 16, v45
	v_and_b32_e32 v45, 0xffff0000, v45
	v_lshlrev_b32_e32 v62, 16, v46
	v_and_b32_e32 v63, 0xffff0000, v46
	v_lshlrev_b32_e32 v46, 16, v47
	v_and_b32_e32 v47, 0xffff0000, v47
	v_pk_add_f32 v[14:15], v[14:15], v[40:41]
	v_pk_add_f32 v[12:13], v[12:13], v[56:57]
	v_pk_add_f32 v[10:11], v[10:11], v[42:43]
	v_pk_add_f32 v[8:9], v[8:9], v[58:59]
	global_store_dwordx4 v[54:55], v[0:3], off
	v_lshlrev_b32_e32 v64, 16, v48
	v_and_b32_e32 v65, 0xffff0000, v48
	v_cvt_pk_bf16_f32 v0, v12, v13
	v_cvt_pk_bf16_f32 v1, v14, v15
	v_cvt_pk_bf16_f32 v2, v8, v9
	v_cvt_pk_bf16_f32 v3, v10, v11
	v_lshlrev_b32_e32 v48, 16, v49
	v_and_b32_e32 v49, 0xffff0000, v49
	v_pk_add_f32 v[22:23], v[22:23], v[44:45]
	v_pk_add_f32 v[20:21], v[20:21], v[60:61]
	v_pk_add_f32 v[18:19], v[18:19], v[46:47]
	v_pk_add_f32 v[16:17], v[16:17], v[62:63]
	global_store_dwordx4 v[54:55], v[0:3], off offset:256
	v_pk_add_f32 v[6:7], v[6:7], v[48:49]
	v_pk_add_f32 v[4:5], v[4:5], v[64:65]
	v_cvt_pk_bf16_f32 v0, v20, v21
	v_cvt_pk_bf16_f32 v1, v22, v23
	v_cvt_pk_bf16_f32 v2, v16, v17
	v_cvt_pk_bf16_f32 v3, v18, v19
	global_store_dwordx4 v[52:53], v[0:3], off
	s_nop 1
	v_cvt_pk_bf16_f32 v0, v4, v5
	v_cvt_pk_bf16_f32 v1, v6, v7
	v_cvt_pk_bf16_f32 v2, v34, v35
	v_cvt_pk_bf16_f32 v3, v32, v33
	global_store_dwordx4 v[52:53], v[0:3], off offset:256
	s_cbranch_vccnz .LBB0_1600
	s_andn2_b64 vcc, exec, s[4:5]
	s_cbranch_vccnz .LBB0_1599
	s_barrier
	s_branch .LBB0_1599

; __device__ __forceinline__ unsigned cvtpk(float lo, float hi) { unsigned r; asm volatile("v_cvt_pk_bf16_f32 %0, %1, %2" : "=v"(r) : "v"(lo), "v"(hi)); return r; }
;     __device__ __forceinline__ float* out() const { return (float*)(__attribute__((address_space(1))) float*)get(20); }
;     __device__ __forceinline__ void operator()(const f32x4 (&acc)[2][2][4][2], const Unit& u, int wr, int wc, int fr, int fq) const {
;         const int row0 = u.pm * BM + wr * 64 + fr, col0 = u.pn * BM + wc * 32 + 8 * fq;
; #pragma unroll
;         for (int ai = 0; ai < 2; ++ai)
; #pragma unroll
;             for (int mp = 0; mp < 2; ++mp) {
;                 f32x4 b0[2][2], b1[2][2];
; #pragma unroll
;                 for (int mm = 0; mm < 2; ++mm)
; #pragma unroll
;                     for (int bj = 0; bj < 2; ++bj) { const size_t off = (size_t)(row0 + ai * HALF + (2 * mp + mm) * 16) * 2048 + col0 + bj * HALF;
;                         if (BASE_BF) { const u32x4 w = *(const u32x4*)((const bf16*)base + off);
;                             b0[mm][bj] = (f32x4){bflo(w.x), bfhi(w.x), bflo(w.y), bfhi(w.y)}; b1[mm][bj] = (f32x4){bflo(w.z), bfhi(w.z), bflo(w.w), bfhi(w.w)}; }
;                         else { b0[mm][bj] = __builtin_nontemporal_load((const f32x4*)((const float*)base + off)); b1[mm][bj] = __builtin_nontemporal_load((const f32x4*)((const float*)base + off + 4)); } }
; #pragma unroll
;                 for (int mm = 0; mm < 2; ++mm)
; #pragma unroll
;                     for (int bj = 0; bj < 2; ++bj) { const int m = 2 * mp + mm; const size_t off = (size_t)(row0 + ai * HALF + m * 16) * 2048 + col0 + bj * HALF;
;                         const f32x4 v0 = b0[mm][bj] + acc[ai][bj][m][0], v1 = b1[mm][bj] + acc[ai][bj][m][1];
;                         if (OUT_BF) { u32x4 w; w.x = cvtpk(v0[0], v0[1]); w.y = cvtpk(v0[2], v0[3]); w.z = cvtpk(v1[0], v1[1]); w.w = cvtpk(v1[2], v1[3]); *(u32x4*)((bf16*)out + off) = w; }
;                         else { *(f32x4*)((float*)out + off) = v0; *(f32x4*)((float*)out + off + 4) = v1; } }
;             }
;     }
.LBB0_1811:
	v_lshl_add_u32 v146, s44, 8, v150
	v_lshl_or_b32 v148, s45, 8, v152
	v_ashrrev_i32_e32 v149, 31, v148
	v_ashrrev_i32_e32 v147, 31, v146
	v_lshl_add_u64 v[144:145], v[148:149], 1, s[6:7]
	v_lshlrev_b64 v[156:157], 12, v[146:147]
	v_or_b32_e32 v172, 16, v146
	v_lshl_add_u64 v[160:161], v[144:145], 0, v[156:157]
	v_ashrrev_i32_e32 v173, 31, v172
	s_mov_b32 s81, 0
	s_mov_b32 s80, 0x20000
	v_lshl_add_u64 v[248:249], v[160:161], 0, s[80:81]
	global_load_dwordx4 v[198:201], v[248:249], off
	global_load_dwordx4 v[206:209], v[248:249], off offset:256
	s_mov_b32 s80, 0x30000
	v_lshl_add_u64 v[248:249], v[160:161], 0, s[80:81]
	global_load_dwordx4 v[210:213], v[248:249], off
	global_load_dwordx4 v[214:217], v[248:249], off offset:256
	s_mov_b32 s80, 0x80000
	v_lshl_add_u64 v[248:249], v[160:161], 0, s[80:81]
	global_load_dwordx4 v[218:221], v[248:249], off
	global_load_dwordx4 v[222:225], v[248:249], off offset:256
	s_mov_b32 s80, 0x90000
	v_lshl_add_u64 v[248:249], v[160:161], 0, s[80:81]
	global_load_dwordx4 v[226:229], v[248:249], off
	global_load_dwordx4 v[232:235], v[248:249], off offset:256
	s_mov_b32 s80, 0xa0000
	v_lshl_add_u64 v[248:249], v[160:161], 0, s[80:81]
	global_load_dwordx4 v[236:239], v[248:249], off
	global_load_dwordx4 v[240:243], v[248:249], off offset:256
	s_mov_b32 s80, 0xb0000
	v_lshl_add_u64 v[248:249], v[160:161], 0, s[80:81]
	global_load_dwordx4 v[244:247], v[248:249], off
	global_load_dwordx4 v[250:253], v[248:249], off offset:256
	global_load_dwordx4 v[156:159], v[160:161], off
	s_nop 0
	global_load_dwordx4 v[160:163], v[160:161], off offset:256
	v_lshlrev_b64 v[164:165], 12, v[172:173]
	v_lshl_add_u64 v[168:169], v[144:145], 0, v[164:165]
	global_load_dwordx4 v[164:167], v[168:169], off
	s_nop 0
	global_load_dwordx4 v[168:171], v[168:169], off offset:256
	v_lshlrev_b64 v[176:177], 13, v[146:147]
	v_lshlrev_b64 v[148:149], 2, v[148:149]
	v_lshl_add_u64 v[176:177], s[2:3], 0, v[176:177]
	v_lshlrev_b64 v[172:173], 13, v[172:173]
	v_lshl_add_u64 v[176:177], v[176:177], 0, v[148:149]
	v_or_b32_e32 v174, 32, v146
	v_lshl_add_u64 v[172:173], s[2:3], 0, v[172:173]
	v_ashrrev_i32_e32 v175, 31, v174
	v_lshl_add_u64 v[172:173], v[172:173], 0, v[148:149]
	v_lshlrev_b64 v[178:179], 12, v[174:175]
	v_lshl_add_u64 v[178:179], v[144:145], 0, v[178:179]
	s_andn2_b64 vcc, exec, s[0:1]
	s_mov_b64 s[0:1], -1
	s_waitcnt vmcnt(0)
	v_lshlrev_b32_e32 v180, 16, v156
	v_and_b32_e32 v181, 0xffff0000, v156
	v_lshlrev_b32_e32 v156, 16, v157
	v_and_b32_e32 v157, 0xffff0000, v157
	v_lshlrev_b32_e32 v184, 16, v160
	v_and_b32_e32 v185, 0xffff0000, v160
	v_lshlrev_b32_e32 v182, 16, v158
	v_and_b32_e32 v183, 0xffff0000, v158
	v_lshlrev_b32_e32 v158, 16, v159
	v_and_b32_e32 v159, 0xffff0000, v159
	v_lshlrev_b32_e32 v160, 16, v161
	v_and_b32_e32 v161, 0xffff0000, v161
	v_lshlrev_b32_e32 v186, 16, v162
	v_and_b32_e32 v187, 0xffff0000, v162
	v_lshlrev_b32_e32 v162, 16, v163
	v_and_b32_e32 v163, 0xffff0000, v163
	v_lshlrev_b32_e32 v190, 16, v166
	v_and_b32_e32 v191, 0xffff0000, v166
	v_pk_add_f32 v[126:127], v[126:127], v[156:157]
	v_pk_add_f32 v[124:125], v[124:125], v[180:181]
	v_pk_add_f32 v[108:109], v[108:109], v[184:185]
	v_lshlrev_b32_e32 v188, 16, v164
	v_and_b32_e32 v189, 0xffff0000, v164
	v_lshlrev_b32_e32 v164, 16, v165
	v_and_b32_e32 v165, 0xffff0000, v165
	v_pk_add_f32 v[122:123], v[122:123], v[158:159]
	v_pk_add_f32 v[120:121], v[120:121], v[182:183]
	v_pk_add_f32 v[110:111], v[110:111], v[160:161]
	v_pk_add_f32 v[106:107], v[106:107], v[162:163]
	v_pk_add_f32 v[104:105], v[104:105], v[186:187]
	global_store_dwordx4 v[176:177], v[124:127], off
	global_store_dwordx4 v[176:177], v[120:123], off offset:16
	global_store_dwordx4 v[176:177], v[108:111], off offset:512
	global_store_dwordx4 v[176:177], v[104:107], off offset:528
	v_lshlrev_b32_e32 v166, 16, v167
	v_pk_add_f32 v[108:109], v[112:113], v[190:191]
	v_or_b32_e32 v112, 48, v146
	v_and_b32_e32 v167, 0xffff0000, v167
	v_lshlrev_b32_e32 v192, 16, v168
	v_and_b32_e32 v193, 0xffff0000, v168
	v_lshlrev_b32_e32 v168, 16, v169
	v_and_b32_e32 v169, 0xffff0000, v169
	v_lshlrev_b32_e32 v194, 16, v170
	v_and_b32_e32 v195, 0xffff0000, v170
	v_lshlrev_b32_e32 v170, 16, v171
	v_and_b32_e32 v171, 0xffff0000, v171
	v_pk_add_f32 v[106:107], v[118:119], v[164:165]
	v_pk_add_f32 v[104:105], v[116:117], v[188:189]
	v_ashrrev_i32_e32 v113, 31, v112
	v_pk_add_f32 v[110:111], v[114:115], v[166:167]
	v_pk_add_f32 v[102:103], v[102:103], v[168:169]
	v_pk_add_f32 v[100:101], v[100:101], v[192:193]
	v_pk_add_f32 v[98:99], v[98:99], v[170:171]
	v_pk_add_f32 v[96:97], v[96:97], v[194:195]
	global_store_dwordx4 v[172:173], v[104:107], off
	global_store_dwordx4 v[172:173], v[108:111], off offset:16
	global_store_dwordx4 v[172:173], v[100:103], off offset:512
	global_store_dwordx4 v[172:173], v[96:99], off offset:528
	v_lshlrev_b64 v[104:105], 12, v[112:113]
	v_lshl_add_u64 v[108:109], v[144:145], 0, v[104:105]
	global_load_dwordx4 v[96:99], v[178:179], off
	global_load_dwordx4 v[100:103], v[178:179], off offset:256
	global_load_dwordx4 v[104:107], v[108:109], off
	s_nop 0
	global_load_dwordx4 v[108:111], v[108:109], off offset:256
	v_lshlrev_b64 v[116:117], 13, v[174:175]
	v_lshlrev_b64 v[112:113], 13, v[112:113]
	v_lshl_add_u64 v[116:117], s[2:3], 0, v[116:117]
	v_lshl_add_u64 v[112:113], s[2:3], 0, v[112:113]
	v_lshl_add_u64 v[116:117], v[116:117], 0, v[148:149]
	v_add_u32_e32 v114, 0x80, v146
	v_lshl_add_u64 v[112:113], v[112:113], 0, v[148:149]
	v_ashrrev_i32_e32 v115, 31, v114
	v_lshlrev_b64 v[118:119], 12, v[114:115]
	v_lshl_add_u64 v[118:119], v[144:145], 0, v[118:119]
	s_waitcnt vmcnt(3)
; __device__ __forceinline__ unsigned cvtpk(float lo, float hi) { unsigned r; asm volatile("v_cvt_pk_bf16_f32 %0, %1, %2" : "=v"(r) : "v"(lo), "v"(hi)); return r; }
;     __device__ __forceinline__ float* out() const { return (float*)(__attribute__((address_space(1))) float*)get(20); }
;     __device__ __forceinline__ void operator()(const f32x4 (&acc)[2][2][4][2], const Unit& u, int wr, int wc, int fr, int fq) const {
;     ...
;             for (int mp = 0; mp < 2; ++mp) {
;                 f32x4 b0[2][2], b1[2][2];
; #pragma unroll
;                 for (int mm = 0; mm < 2; ++mm)
; #pragma unroll
;                     for (int bj = 0; bj < 2; ++bj) { const size_t off = (size_t)(row0 + ai * HALF + (2 * mp + mm) * 16) * 2048 + col0 + bj * HALF;
;                         if (BASE_BF) { const u32x4 w = *(const u32x4*)((const bf16*)base + off);
;                             b0[mm][bj] = (f32x4){bflo(w.x), bfhi(w.x), bflo(w.y), bfhi(w.y)}; b1[mm][bj] = (f32x4){bflo(w.z), bfhi(w.z), bflo(w.w), bfhi(w.w)}; }
;                         else { b0[mm][bj] = __builtin_nontemporal_load((const f32x4*)((const float*)base + off)); b1[mm][bj] = __builtin_nontemporal_load((const f32x4*)((const float*)base + off + 4)); } }
; #pragma unroll
;                 for (int mm = 0; mm < 2; ++mm)
; #pragma unroll
;                     for (int bj = 0; bj < 2; ++bj) { const int m = 2 * mp + mm; const size_t off = (size_t)(row0 + ai * HALF + m * 16) * 2048 + col0 + bj * HALF;
;                         const f32x4 v0 = b0[mm][bj] + acc[ai][bj][m][0], v1 = b1[mm][bj] + acc[ai][bj][m][1];
;                         if (OUT_BF) { u32x4 w; w.x = cvtpk(v0[0], v0[1]); w.y = cvtpk(v0[2], v0[3]); w.z = cvtpk(v1[0], v1[1]); w.w = cvtpk(v1[2], v1[3]); *(u32x4*)((bf16*)out + off) = w; }
;                         else { *(f32x4*)((float*)out + off) = v0; *(f32x4*)((float*)out + off + 4) = v1; } }
	v_lshlrev_b32_e32 v120, 16, v96
	v_and_b32_e32 v121, 0xffff0000, v96
	v_lshlrev_b32_e32 v96, 16, v97
	v_and_b32_e32 v97, 0xffff0000, v97
	s_waitcnt vmcnt(1)
	v_lshlrev_b32_e32 v158, 16, v106
	v_and_b32_e32 v159, 0xffff0000, v106
	v_lshlrev_b32_e32 v122, 16, v98
	v_and_b32_e32 v123, 0xffff0000, v98
	v_lshlrev_b32_e32 v98, 16, v99
	v_and_b32_e32 v99, 0xffff0000, v99
	v_lshlrev_b32_e32 v124, 16, v100
	v_and_b32_e32 v125, 0xffff0000, v100
	v_lshlrev_b32_e32 v100, 16, v101
	v_and_b32_e32 v101, 0xffff0000, v101
	v_lshlrev_b32_e32 v126, 16, v102
	v_and_b32_e32 v127, 0xffff0000, v102
	v_lshlrev_b32_e32 v102, 16, v103
	v_and_b32_e32 v103, 0xffff0000, v103
	v_lshlrev_b32_e32 v156, 16, v104
	v_and_b32_e32 v157, 0xffff0000, v104
	v_lshlrev_b32_e32 v104, 16, v105
	v_and_b32_e32 v105, 0xffff0000, v105
	v_lshlrev_b32_e32 v106, 16, v107
	v_and_b32_e32 v107, 0xffff0000, v107
	s_waitcnt vmcnt(0)
	v_lshlrev_b32_e32 v160, 16, v108
	v_and_b32_e32 v161, 0xffff0000, v108
	v_lshlrev_b32_e32 v108, 16, v109
	v_and_b32_e32 v109, 0xffff0000, v109
	v_lshlrev_b32_e32 v162, 16, v110
	v_and_b32_e32 v163, 0xffff0000, v110
	v_lshlrev_b32_e32 v110, 16, v111
	v_and_b32_e32 v111, 0xffff0000, v111
	v_pk_add_f32 v[94:95], v[94:95], v[96:97]
	v_pk_add_f32 v[92:93], v[92:93], v[120:121]
	v_pk_add_f32 v[80:81], v[80:81], v[158:159]
	v_pk_add_f32 v[90:91], v[90:91], v[98:99]
	v_pk_add_f32 v[88:89], v[88:89], v[122:123]
	v_pk_add_f32 v[78:79], v[78:79], v[100:101]
	v_pk_add_f32 v[76:77], v[76:77], v[124:125]
	v_pk_add_f32 v[74:75], v[74:75], v[102:103]
	v_pk_add_f32 v[72:73], v[72:73], v[126:127]
	v_pk_add_f32 v[86:87], v[86:87], v[104:105]
	v_pk_add_f32 v[84:85], v[84:85], v[156:157]
	v_pk_add_f32 v[82:83], v[82:83], v[106:107]
	v_pk_add_f32 v[70:71], v[70:71], v[108:109]
	v_pk_add_f32 v[68:69], v[68:69], v[160:161]
	v_pk_add_f32 v[66:67], v[66:67], v[110:111]
	v_pk_add_f32 v[64:65], v[64:65], v[162:163]
	global_store_dwordx4 v[116:117], v[92:95], off
	global_store_dwordx4 v[116:117], v[88:91], off offset:16
	global_store_dwordx4 v[116:117], v[76:79], off offset:512
	global_store_dwordx4 v[116:117], v[72:75], off offset:528
	global_store_dwordx4 v[112:113], v[84:87], off
	global_store_dwordx4 v[112:113], v[80:83], off offset:16
	global_store_dwordx4 v[112:113], v[68:71], off offset:512
	global_store_dwordx4 v[112:113], v[64:67], off offset:528
	v_add_u32_e32 v80, 0x90, v146
	v_ashrrev_i32_e32 v81, 31, v80
	v_lshlrev_b64 v[72:73], 12, v[80:81]
	v_lshl_add_u64 v[82:83], v[144:145], 0, v[72:73]
	global_load_dwordx4 v[64:67], v[118:119], off
	global_load_dwordx4 v[68:71], v[118:119], off offset:256
	global_load_dwordx4 v[72:75], v[82:83], off
	global_load_dwordx4 v[76:79], v[82:83], off offset:256
	v_lshlrev_b64 v[84:85], 13, v[114:115]
	v_lshlrev_b64 v[80:81], 13, v[80:81]
	v_lshl_add_u64 v[84:85], s[2:3], 0, v[84:85]
	v_lshl_add_u64 v[80:81], s[2:3], 0, v[80:81]
	v_lshl_add_u64 v[84:85], v[84:85], 0, v[148:149]
	v_add_u32_e32 v82, 0xa0, v146
	v_lshl_add_u64 v[80:81], v[80:81], 0, v[148:149]
	v_ashrrev_i32_e32 v83, 31, v82
	v_lshlrev_b64 v[86:87], 12, v[82:83]
	v_lshl_add_u64 v[86:87], v[144:145], 0, v[86:87]
	s_waitcnt vmcnt(3)
	v_lshlrev_b32_e32 v88, 16, v64
	v_and_b32_e32 v89, 0xffff0000, v64
	v_lshlrev_b32_e32 v64, 16, v65
	v_and_b32_e32 v65, 0xffff0000, v65
	s_waitcnt vmcnt(1)
	v_lshlrev_b32_e32 v98, 16, v74
	v_and_b32_e32 v99, 0xffff0000, v74
	v_lshlrev_b32_e32 v90, 16, v66
	v_and_b32_e32 v91, 0xffff0000, v66
	v_lshlrev_b32_e32 v66, 16, v67
	v_and_b32_e32 v67, 0xffff0000, v67
	v_lshlrev_b32_e32 v92, 16, v68
	v_and_b32_e32 v93, 0xffff0000, v68
	v_lshlrev_b32_e32 v68, 16, v69
	v_and_b32_e32 v69, 0xffff0000, v69
	v_lshlrev_b32_e32 v94, 16, v70
	v_and_b32_e32 v95, 0xffff0000, v70
	v_lshlrev_b32_e32 v70, 16, v71
	v_and_b32_e32 v71, 0xffff0000, v71
	v_lshlrev_b32_e32 v96, 16, v72
	v_and_b32_e32 v97, 0xffff0000, v72
	v_lshlrev_b32_e32 v72, 16, v73
	v_and_b32_e32 v73, 0xffff0000, v73
	v_lshlrev_b32_e32 v74, 16, v75
	v_and_b32_e32 v75, 0xffff0000, v75
	s_waitcnt vmcnt(0)
;     __device__ __forceinline__ void operator()(const f32x4 (&acc)[2][2][4][2], const Unit& u, int wr, int wc, int fr, int fq) const {
;     ...
;             for (int mp = 0; mp < 2; ++mp) {
;                 f32x4 b0[2][2], b1[2][2];
; #pragma unroll
;                 for (int mm = 0; mm < 2; ++mm)
; #pragma unroll
;                     for (int bj = 0; bj < 2; ++bj) { const size_t off = (size_t)(row0 + ai * HALF + (2 * mp + mm) * 16) * 2048 + col0 + bj * HALF;
;                         if (BASE_BF) { const u32x4 w = *(const u32x4*)((const bf16*)base + off);
;                             b0[mm][bj] = (f32x4){bflo(w.x), bfhi(w.x), bflo(w.y), bfhi(w.y)}; b1[mm][bj] = (f32x4){bflo(w.z), bfhi(w.z), bflo(w.w), bfhi(w.w)}; }
;                         else { b0[mm][bj] = __builtin_nontemporal_load((const f32x4*)((const float*)base + off)); b1[mm][bj] = __builtin_nontemporal_load((const f32x4*)((const float*)base + off + 4)); } }
; #pragma unroll
;                 for (int mm = 0; mm < 2; ++mm)
; #pragma unroll
;                     for (int bj = 0; bj < 2; ++bj) { const int m = 2 * mp + mm; const size_t off = (size_t)(row0 + ai * HALF + m * 16) * 2048 + col0 + bj * HALF;
;                         const f32x4 v0 = b0[mm][bj] + acc[ai][bj][m][0], v1 = b1[mm][bj] + acc[ai][bj][m][1];
;                         if (OUT_BF) { u32x4 w; w.x = cvtpk(v0[0], v0[1]); w.y = cvtpk(v0[2], v0[3]); w.z = cvtpk(v1[0], v1[1]); w.w = cvtpk(v1[2], v1[3]); *(u32x4*)((bf16*)out + off) = w; }
;                         else { *(f32x4*)((float*)out + off) = v0; *(f32x4*)((float*)out + off + 4) = v1; } }
; template <class Epi, class Sched, bool ALIGN_EPI = false, bool SP2 = false>
; __device__ __forceinline__ void gemm_phase(PG8_LAS unsigned char* lds, const Gemm g, const Sched& S, const Epi& E, const int wv0) {
;     ...
;         if constexpr (epi_keeps_acc<Epi>::value) { E.mid(acc, cur, wr, wc, fr, fq); } else if constexpr (!Epi::AFTER_DRAIN) { E(acc, cur, wr, wc, fr, fq); }
;         if (!has_next) break;
;         if constexpr (!epi_keeps_acc<Epi>::value) {
; #pragma unroll
;         for (int a = 0; a < 2; ++a)
; #pragma unroll
;             for (int b = 0; b < 2; ++b)
; #pragma unroll
;                 for (int m = 0; m < 4; ++m)
; #pragma unroll
;                     for (int n = 0; n < 2; ++n) acc[a][b][m][n] = (f32x4){0.f, 0.f, 0.f, 0.f};
;         }
;         cur = nxt; cA = nA; cB = nB; ++ui;
	v_lshlrev_b32_e32 v100, 16, v76
	v_and_b32_e32 v101, 0xffff0000, v76
	v_lshlrev_b32_e32 v76, 16, v77
	v_and_b32_e32 v77, 0xffff0000, v77
	v_lshlrev_b32_e32 v102, 16, v78
	v_and_b32_e32 v103, 0xffff0000, v78
	v_lshlrev_b32_e32 v78, 16, v79
	v_and_b32_e32 v79, 0xffff0000, v79
	v_pk_add_f32 v[62:63], v[62:63], v[64:65]
	v_pk_add_f32 v[60:61], v[60:61], v[88:89]
	v_pk_add_f32 v[48:49], v[48:49], v[98:99]
	v_pk_add_f32 v[58:59], v[58:59], v[66:67]
	v_pk_add_f32 v[56:57], v[56:57], v[90:91]
	v_pk_add_f32 v[46:47], v[46:47], v[68:69]
	v_pk_add_f32 v[44:45], v[44:45], v[92:93]
	v_pk_add_f32 v[42:43], v[42:43], v[70:71]
	v_pk_add_f32 v[40:41], v[40:41], v[94:95]
	v_pk_add_f32 v[54:55], v[54:55], v[72:73]
	v_pk_add_f32 v[52:53], v[52:53], v[96:97]
	v_pk_add_f32 v[50:51], v[50:51], v[74:75]
	v_pk_add_f32 v[38:39], v[38:39], v[76:77]
	v_pk_add_f32 v[36:37], v[36:37], v[100:101]
	v_pk_add_f32 v[34:35], v[34:35], v[78:79]
	v_pk_add_f32 v[32:33], v[32:33], v[102:103]
	global_store_dwordx4 v[84:85], v[60:63], off
	global_store_dwordx4 v[84:85], v[56:59], off offset:16
	global_store_dwordx4 v[84:85], v[44:47], off offset:512
	global_store_dwordx4 v[84:85], v[40:43], off offset:528
	global_store_dwordx4 v[80:81], v[52:55], off
	global_store_dwordx4 v[80:81], v[48:51], off offset:16
	global_store_dwordx4 v[80:81], v[36:39], off offset:512
	global_store_dwordx4 v[80:81], v[32:35], off offset:528
	v_add_u32_e32 v48, 0xb0, v146
	v_ashrrev_i32_e32 v49, 31, v48
	v_lshlrev_b64 v[40:41], 12, v[48:49]
	v_lshl_add_u64 v[50:51], v[144:145], 0, v[40:41]
	global_load_dwordx4 v[32:35], v[86:87], off
	global_load_dwordx4 v[36:39], v[86:87], off offset:256
	global_load_dwordx4 v[40:43], v[50:51], off
	global_load_dwordx4 v[44:47], v[50:51], off offset:256
	v_lshlrev_b64 v[50:51], 13, v[82:83]
	v_lshlrev_b64 v[48:49], 13, v[48:49]
	v_lshl_add_u64 v[50:51], s[2:3], 0, v[50:51]
	v_lshl_add_u64 v[48:49], s[2:3], 0, v[48:49]
	v_lshl_add_u64 v[50:51], v[50:51], 0, v[148:149]
	v_lshl_add_u64 v[48:49], v[48:49], 0, v[148:149]
	s_waitcnt vmcnt(3)
	v_lshlrev_b32_e32 v52, 16, v32
	v_and_b32_e32 v53, 0xffff0000, v32
	v_lshlrev_b32_e32 v32, 16, v33
	v_and_b32_e32 v33, 0xffff0000, v33
	v_lshlrev_b32_e32 v54, 16, v34
	v_and_b32_e32 v55, 0xffff0000, v34
	v_lshlrev_b32_e32 v34, 16, v35
	v_and_b32_e32 v35, 0xffff0000, v35
	s_waitcnt vmcnt(2)
	v_lshlrev_b32_e32 v56, 16, v36
	v_and_b32_e32 v57, 0xffff0000, v36
	v_lshlrev_b32_e32 v36, 16, v37
	v_and_b32_e32 v37, 0xffff0000, v37
	v_lshlrev_b32_e32 v58, 16, v38
	v_and_b32_e32 v59, 0xffff0000, v38
	v_lshlrev_b32_e32 v38, 16, v39
	v_and_b32_e32 v39, 0xffff0000, v39
	s_waitcnt vmcnt(1)
	v_lshlrev_b32_e32 v60, 16, v40
	v_and_b32_e32 v61, 0xffff0000, v40
	v_lshlrev_b32_e32 v40, 16, v41
	v_and_b32_e32 v41, 0xffff0000, v41
	v_lshlrev_b32_e32 v62, 16, v42
	v_and_b32_e32 v63, 0xffff0000, v42
	v_lshlrev_b32_e32 v42, 16, v43
	v_and_b32_e32 v43, 0xffff0000, v43
	s_waitcnt vmcnt(0)
	v_lshlrev_b32_e32 v64, 16, v44
	v_and_b32_e32 v65, 0xffff0000, v44
	v_lshlrev_b32_e32 v44, 16, v45
	v_and_b32_e32 v45, 0xffff0000, v45
	v_lshlrev_b32_e32 v66, 16, v46
	v_and_b32_e32 v67, 0xffff0000, v46
	v_lshlrev_b32_e32 v46, 16, v47
	v_and_b32_e32 v47, 0xffff0000, v47
	v_pk_add_f32 v[30:31], v[30:31], v[32:33]
	v_pk_add_f32 v[28:29], v[28:29], v[52:53]
	v_pk_add_f32 v[26:27], v[26:27], v[34:35]
	v_pk_add_f32 v[24:25], v[24:25], v[54:55]
	v_pk_add_f32 v[14:15], v[14:15], v[36:37]
	v_pk_add_f32 v[12:13], v[12:13], v[56:57]
	v_pk_add_f32 v[10:11], v[10:11], v[38:39]
	v_pk_add_f32 v[8:9], v[8:9], v[58:59]
	v_pk_add_f32 v[22:23], v[22:23], v[40:41]
	v_pk_add_f32 v[20:21], v[20:21], v[60:61]
	v_pk_add_f32 v[18:19], v[18:19], v[42:43]
	v_pk_add_f32 v[16:17], v[16:17], v[62:63]
	v_pk_add_f32 v[6:7], v[6:7], v[44:45]
	v_pk_add_f32 v[4:5], v[4:5], v[64:65]
	v_pk_add_f32 v[2:3], v[2:3], v[46:47]
	v_pk_add_f32 v[0:1], v[0:1], v[66:67]
	global_store_dwordx4 v[50:51], v[28:31], off
	global_store_dwordx4 v[50:51], v[24:27], off offset:16
	global_store_dwordx4 v[50:51], v[12:15], off offset:512
	global_store_dwordx4 v[50:51], v[8:11], off offset:528
	global_store_dwordx4 v[48:49], v[20:23], off
	global_store_dwordx4 v[48:49], v[16:19], off offset:16
	global_store_dwordx4 v[48:49], v[4:7], off offset:512
	global_store_dwordx4 v[48:49], v[0:3], off offset:528
	s_cbranch_vccnz .LBB0_1800
	s_andn2_b64 vcc, exec, s[4:5]
	s_cbranch_vccnz .LBB0_1799
	s_barrier
	s_branch .LBB0_1799
